# P0 mod_item: eight w_mod row loads of a trip issued together (on top of v21)
# baseline (speedup 1.0000x reference)
; __device__ __forceinline__ void mod_item(const Params& p, int item, char* lds) {
;     ...
; #pragma unroll 2
;   for (int k = k0; k < k0 + 32; k += 4) {
;     const size_t kg = (size_t)(kq * 256 + k);
;     const float w0 = wmod[kg * 6144 + col], w1 = wmod[(kg + 1) * 6144 + col];
;     const float w2 = wmod[(kg + 2) * 6144 + col], w3 = wmod[(kg + 3) * 6144 + col];
; #pragma unroll
;     for (int b = 0; b < 33; ++b) {
;       const float4 sv = *(const float4*)(s + b * 256 + k);
;       acc[b] += sv.x * w0 + sv.y * w1 + sv.z * w2 + sv.w * w3;
;     }
;   }
.LBB0_22:
	v_add_u32_e32 v57, 8, v57
	v_add_co_u32_e32 v2, vcc, s42, v16
	s_nop 1
	v_addc_co_u32_e32 v3, vcc, -1, v17, vcc
	global_load_dword v20, v[2:3], off
	v_add_co_u32_e32 v2, vcc, s43, v16
	s_nop 1
	v_addc_co_u32_e32 v3, vcc, -1, v17, vcc
	global_load_dword v21, v[2:3], off
	v_add_co_u32_e32 v2, vcc, s44, v16
	s_nop 1
	v_addc_co_u32_e32 v3, vcc, -1, v17, vcc
	global_load_dword v22, v[2:3], off
	v_add_co_u32_e32 v2, vcc, s45, v16
	s_nop 1
	v_addc_co_u32_e32 v3, vcc, -1, v17, vcc
	global_load_dword v23, v[2:3], off
	v_add_co_u32_e32 v2, vcc, s46, v16
	s_nop 1
	v_addc_co_u32_e32 v3, vcc, -1, v17, vcc
	global_load_dword v240, v[2:3], off
	v_add_co_u32_e32 v2, vcc, s47, v16
	s_nop 1
	v_addc_co_u32_e32 v3, vcc, -1, v17, vcc
	global_load_dword v241, v[2:3], off
	v_add_co_u32_e32 v2, vcc, s50, v16
	s_nop 1
	v_addc_co_u32_e32 v3, vcc, -1, v17, vcc
	global_load_dword v242, v[2:3], off
	global_load_dword v243, v[16:17], off
	ds_read_b128 v[6:9], v58
	ds_read_b128 v[2:5], v58 offset:16
	s_waitcnt vmcnt(4)
	v_mov_b32_e32 v12, v21
	s_waitcnt lgkmcnt(1)
	v_pk_mul_f32 v[6:7], v[20:21], v[6:7]
	s_nop 0
	v_add_f32_e32 v6, v6, v7
	v_pk_mul_f32 v[8:9], v[22:23], v[8:9]
	s_nop 0
	v_add_f32_e32 v6, v6, v8
	v_add_f32_e32 v6, v6, v9
	v_add_f32_e32 v59, v59, v6
	ds_read_b128 v[6:9], v58 offset:1024
	ds_read_b128 v[60:63], v58 offset:2048
	v_mov_b32_e32 v54, v23
	s_waitcnt lgkmcnt(1)
	v_mov_b32_e32 v65, v6
	s_waitcnt lgkmcnt(0)
	v_mov_b32_e32 v6, v61
	v_mov_b32_e32 v64, v60
	v_pk_mul_f32 v[6:7], v[12:13], v[6:7] op_sel_hi:[0,1]
	v_pk_fma_f32 v[6:7], v[20:21], v[64:65], v[6:7] op_sel_hi:[0,1,1]
	v_mov_b32_e32 v60, v62
	v_mov_b32_e32 v61, v8
	v_pk_fma_f32 v[6:7], v[22:23], v[60:61], v[6:7] op_sel_hi:[0,1,1]
	v_mov_b32_e32 v8, v63
	v_pk_fma_f32 v[6:7], v[54:55], v[8:9], v[6:7] op_sel_hi:[0,1,1]
	v_pk_add_f32 v[24:25], v[24:25], v[6:7]
	ds_read_b128 v[6:9], v58 offset:3072
	ds_read_b128 v[60:63], v58 offset:4096
	s_waitcnt lgkmcnt(1)
	v_mov_b32_e32 v65, v6
	s_waitcnt lgkmcnt(0)
	v_mov_b32_e32 v6, v61
	v_mov_b32_e32 v64, v60
	v_pk_mul_f32 v[6:7], v[12:13], v[6:7] op_sel_hi:[0,1]
	v_pk_fma_f32 v[6:7], v[20:21], v[64:65], v[6:7] op_sel_hi:[0,1,1]
	v_mov_b32_e32 v60, v62
	v_mov_b32_e32 v61, v8
	v_pk_fma_f32 v[6:7], v[22:23], v[60:61], v[6:7] op_sel_hi:[0,1,1]
	v_mov_b32_e32 v8, v63
	v_pk_fma_f32 v[6:7], v[54:55], v[8:9], v[6:7] op_sel_hi:[0,1,1]
	v_pk_add_f32 v[26:27], v[26:27], v[6:7]
	ds_read_b128 v[6:9], v58 offset:5120
	ds_read_b128 v[60:63], v58 offset:6144
	s_waitcnt lgkmcnt(1)
	v_mov_b32_e32 v65, v6
	s_waitcnt lgkmcnt(0)
	v_mov_b32_e32 v6, v61
	v_mov_b32_e32 v64, v60
	v_pk_mul_f32 v[6:7], v[12:13], v[6:7] op_sel_hi:[0,1]
	v_pk_fma_f32 v[6:7], v[20:21], v[64:65], v[6:7] op_sel_hi:[0,1,1]
	v_mov_b32_e32 v60, v62
	v_mov_b32_e32 v61, v8
	v_pk_fma_f32 v[6:7], v[22:23], v[60:61], v[6:7] op_sel_hi:[0,1,1]
	v_mov_b32_e32 v8, v63
	v_pk_fma_f32 v[6:7], v[54:55], v[8:9], v[6:7] op_sel_hi:[0,1,1]
	v_pk_add_f32 v[28:29], v[28:29], v[6:7]
	ds_read_b128 v[6:9], v58 offset:7168
	ds_read_b128 v[60:63], v58 offset:8192
	s_waitcnt lgkmcnt(1)
	v_mov_b32_e32 v65, v6
	s_waitcnt lgkmcnt(0)
	v_mov_b32_e32 v6, v61
	v_mov_b32_e32 v64, v60
	v_pk_mul_f32 v[6:7], v[12:13], v[6:7] op_sel_hi:[0,1]
	v_pk_fma_f32 v[6:7], v[20:21], v[64:65], v[6:7] op_sel_hi:[0,1,1]
	v_mov_b32_e32 v60, v62
	v_mov_b32_e32 v61, v8
	v_pk_fma_f32 v[6:7], v[22:23], v[60:61], v[6:7] op_sel_hi:[0,1,1]
	v_mov_b32_e32 v8, v63
	v_pk_fma_f32 v[6:7], v[54:55], v[8:9], v[6:7] op_sel_hi:[0,1,1]
	v_pk_add_f32 v[30:31], v[30:31], v[6:7]
	ds_read_b128 v[6:9], v58 offset:9216
	ds_read_b128 v[60:63], v58 offset:10240
	s_waitcnt lgkmcnt(1)
	v_mov_b32_e32 v65, v6
	s_waitcnt lgkmcnt(0)
	v_mov_b32_e32 v6, v61
	v_mov_b32_e32 v64, v60
	v_pk_mul_f32 v[6:7], v[12:13], v[6:7] op_sel_hi:[0,1]
	v_pk_fma_f32 v[6:7], v[20:21], v[64:65], v[6:7] op_sel_hi:[0,1,1]
	v_mov_b32_e32 v60, v62
	v_mov_b32_e32 v61, v8
	v_pk_fma_f32 v[6:7], v[22:23], v[60:61], v[6:7] op_sel_hi:[0,1,1]
	v_mov_b32_e32 v8, v63
	v_pk_fma_f32 v[6:7], v[54:55], v[8:9], v[6:7] op_sel_hi:[0,1,1]
	v_pk_add_f32 v[32:33], v[32:33], v[6:7]
	ds_read_b128 v[6:9], v58 offset:11264
	ds_read_b128 v[60:63], v58 offset:12288
	s_waitcnt lgkmcnt(1)
	v_mov_b32_e32 v65, v6
	s_waitcnt lgkmcnt(0)
	v_mov_b32_e32 v6, v61
	v_mov_b32_e32 v64, v60
	v_pk_mul_f32 v[6:7], v[12:13], v[6:7] op_sel_hi:[0,1]
	v_pk_fma_f32 v[6:7], v[20:21], v[64:65], v[6:7] op_sel_hi:[0,1,1]
	v_mov_b32_e32 v60, v62
	v_mov_b32_e32 v61, v8
	v_pk_fma_f32 v[6:7], v[22:23], v[60:61], v[6:7] op_sel_hi:[0,1,1]
	v_mov_b32_e32 v8, v63
	v_pk_fma_f32 v[6:7], v[54:55], v[8:9], v[6:7] op_sel_hi:[0,1,1]
	v_pk_add_f32 v[34:35], v[34:35], v[6:7]
	ds_read_b128 v[6:9], v58 offset:13312
	ds_read_b128 v[60:63], v58 offset:14336
	s_waitcnt lgkmcnt(1)
	v_mov_b32_e32 v65, v6
	s_waitcnt lgkmcnt(0)
	v_mov_b32_e32 v6, v61
	v_mov_b32_e32 v64, v60
	v_pk_mul_f32 v[6:7], v[12:13], v[6:7] op_sel_hi:[0,1]
	v_pk_fma_f32 v[6:7], v[20:21], v[64:65], v[6:7] op_sel_hi:[0,1,1]
	v_mov_b32_e32 v60, v62
	v_mov_b32_e32 v61, v8
	v_pk_fma_f32 v[6:7], v[22:23], v[60:61], v[6:7] op_sel_hi:[0,1,1]
	v_mov_b32_e32 v8, v63
	v_pk_fma_f32 v[6:7], v[54:55], v[8:9], v[6:7] op_sel_hi:[0,1,1]
	v_pk_add_f32 v[36:37], v[36:37], v[6:7]
	ds_read_b128 v[6:9], v58 offset:15360
	ds_read_b128 v[60:63], v58 offset:16384
	s_waitcnt lgkmcnt(1)
	v_mov_b32_e32 v65, v6
	s_waitcnt lgkmcnt(0)
	v_mov_b32_e32 v6, v61
	v_mov_b32_e32 v64, v60
	v_pk_mul_f32 v[6:7], v[12:13], v[6:7] op_sel_hi:[0,1]
	v_pk_fma_f32 v[6:7], v[20:21], v[64:65], v[6:7] op_sel_hi:[0,1,1]
	v_mov_b32_e32 v60, v62
	v_mov_b32_e32 v61, v8
	v_pk_fma_f32 v[6:7], v[22:23], v[60:61], v[6:7] op_sel_hi:[0,1,1]
	v_mov_b32_e32 v8, v63
	v_pk_fma_f32 v[6:7], v[54:55], v[8:9], v[6:7] op_sel_hi:[0,1,1]
	v_pk_add_f32 v[40:41], v[40:41], v[6:7]
	ds_read_b128 v[6:9], v58 offset:17408
	ds_read_b128 v[60:63], v58 offset:18432
	s_waitcnt lgkmcnt(1)
; __device__ __forceinline__ void mod_item(const Params& p, int item, char* lds) {
;     ...
; #pragma unroll 2
;   for (int k = k0; k < k0 + 32; k += 4) {
;     const size_t kg = (size_t)(kq * 256 + k);
;     const float w0 = wmod[kg * 6144 + col], w1 = wmod[(kg + 1) * 6144 + col];
;     const float w2 = wmod[(kg + 2) * 6144 + col], w3 = wmod[(kg + 3) * 6144 + col];
; #pragma unroll
;     for (int b = 0; b < 33; ++b) {
;       const float4 sv = *(const float4*)(s + b * 256 + k);
;       acc[b] += sv.x * w0 + sv.y * w1 + sv.z * w2 + sv.w * w3;
;     }
;   }
	v_mov_b32_e32 v65, v6
	s_waitcnt lgkmcnt(0)
	v_mov_b32_e32 v6, v61
	v_mov_b32_e32 v64, v60
	v_pk_mul_f32 v[6:7], v[12:13], v[6:7] op_sel_hi:[0,1]
	v_pk_fma_f32 v[6:7], v[20:21], v[64:65], v[6:7] op_sel_hi:[0,1,1]
	v_mov_b32_e32 v60, v62
	v_mov_b32_e32 v61, v8
	v_pk_fma_f32 v[6:7], v[22:23], v[60:61], v[6:7] op_sel_hi:[0,1,1]
	v_mov_b32_e32 v8, v63
	v_pk_fma_f32 v[6:7], v[54:55], v[8:9], v[6:7] op_sel_hi:[0,1,1]
	v_pk_add_f32 v[42:43], v[42:43], v[6:7]
	ds_read_b128 v[6:9], v58 offset:19456
	ds_read_b128 v[60:63], v58 offset:20480
	s_waitcnt lgkmcnt(1)
	v_mov_b32_e32 v65, v6
	s_waitcnt lgkmcnt(0)
	v_mov_b32_e32 v6, v61
	v_mov_b32_e32 v64, v60
	v_pk_mul_f32 v[6:7], v[12:13], v[6:7] op_sel_hi:[0,1]
	v_pk_fma_f32 v[6:7], v[20:21], v[64:65], v[6:7] op_sel_hi:[0,1,1]
	v_mov_b32_e32 v60, v62
	v_mov_b32_e32 v61, v8
	v_pk_fma_f32 v[6:7], v[22:23], v[60:61], v[6:7] op_sel_hi:[0,1,1]
	v_mov_b32_e32 v8, v63
	v_pk_fma_f32 v[6:7], v[54:55], v[8:9], v[6:7] op_sel_hi:[0,1,1]
	v_pk_add_f32 v[48:49], v[48:49], v[6:7]
	ds_read_b128 v[6:9], v58 offset:21504
	ds_read_b128 v[60:63], v58 offset:22528
	s_waitcnt lgkmcnt(1)
	v_mov_b32_e32 v65, v6
	s_waitcnt lgkmcnt(0)
	v_mov_b32_e32 v6, v61
	v_mov_b32_e32 v64, v60
	v_pk_mul_f32 v[6:7], v[12:13], v[6:7] op_sel_hi:[0,1]
	v_pk_fma_f32 v[6:7], v[20:21], v[64:65], v[6:7] op_sel_hi:[0,1,1]
	v_mov_b32_e32 v60, v62
	v_mov_b32_e32 v61, v8
	v_pk_fma_f32 v[6:7], v[22:23], v[60:61], v[6:7] op_sel_hi:[0,1,1]
	v_mov_b32_e32 v8, v63
	v_pk_fma_f32 v[6:7], v[54:55], v[8:9], v[6:7] op_sel_hi:[0,1,1]
	v_pk_add_f32 v[46:47], v[46:47], v[6:7]
	ds_read_b128 v[6:9], v58 offset:23552
	ds_read_b128 v[60:63], v58 offset:24576
	s_waitcnt lgkmcnt(1)
	v_mov_b32_e32 v65, v6
	s_waitcnt lgkmcnt(0)
	v_mov_b32_e32 v6, v61
	v_mov_b32_e32 v64, v60
	v_pk_mul_f32 v[6:7], v[12:13], v[6:7] op_sel_hi:[0,1]
	v_pk_fma_f32 v[6:7], v[20:21], v[64:65], v[6:7] op_sel_hi:[0,1,1]
	v_mov_b32_e32 v60, v62
	v_mov_b32_e32 v61, v8
	v_pk_fma_f32 v[6:7], v[22:23], v[60:61], v[6:7] op_sel_hi:[0,1,1]
	v_mov_b32_e32 v8, v63
	v_pk_fma_f32 v[6:7], v[54:55], v[8:9], v[6:7] op_sel_hi:[0,1,1]
	v_pk_add_f32 v[44:45], v[44:45], v[6:7]
	ds_read_b128 v[6:9], v58 offset:25600
	ds_read_b128 v[60:63], v58 offset:26624
	s_waitcnt lgkmcnt(1)
	v_mov_b32_e32 v65, v6
	s_waitcnt lgkmcnt(0)
	v_mov_b32_e32 v6, v61
	v_mov_b32_e32 v64, v60
	v_pk_mul_f32 v[6:7], v[12:13], v[6:7] op_sel_hi:[0,1]
	v_pk_fma_f32 v[6:7], v[20:21], v[64:65], v[6:7] op_sel_hi:[0,1,1]
	v_mov_b32_e32 v60, v62
	v_mov_b32_e32 v61, v8
	v_pk_fma_f32 v[6:7], v[22:23], v[60:61], v[6:7] op_sel_hi:[0,1,1]
	v_mov_b32_e32 v8, v63
	v_pk_fma_f32 v[6:7], v[54:55], v[8:9], v[6:7] op_sel_hi:[0,1,1]
	v_pk_add_f32 v[38:39], v[38:39], v[6:7]
	ds_read_b128 v[6:9], v58 offset:27648
	ds_read_b128 v[60:63], v58 offset:28672
	s_waitcnt lgkmcnt(1)
	v_mov_b32_e32 v65, v6
	s_waitcnt lgkmcnt(0)
	v_mov_b32_e32 v6, v61
	v_mov_b32_e32 v64, v60
	v_pk_mul_f32 v[6:7], v[12:13], v[6:7] op_sel_hi:[0,1]
	v_pk_fma_f32 v[6:7], v[20:21], v[64:65], v[6:7] op_sel_hi:[0,1,1]
	v_mov_b32_e32 v60, v62
	v_mov_b32_e32 v61, v8
	v_pk_fma_f32 v[6:7], v[22:23], v[60:61], v[6:7] op_sel_hi:[0,1,1]
	v_mov_b32_e32 v8, v63
	ds_read_b128 v[60:63], v58 offset:29696
	ds_read_b128 v[64:67], v58 offset:30720
	v_pk_fma_f32 v[6:7], v[54:55], v[8:9], v[6:7] op_sel_hi:[0,1,1]
	v_pk_add_f32 v[8:9], v[50:51], v[6:7]
	s_waitcnt lgkmcnt(1)
	v_mov_b32_e32 v7, v60
	s_waitcnt lgkmcnt(0)
	v_mov_b32_e32 v60, v65
	v_mov_b32_e32 v6, v64
	v_pk_mul_f32 v[50:51], v[12:13], v[60:61] op_sel_hi:[0,1]
	v_pk_fma_f32 v[6:7], v[20:21], v[6:7], v[50:51] op_sel_hi:[0,1,1]
	v_mov_b32_e32 v50, v66
	v_mov_b32_e32 v51, v62
	v_pk_fma_f32 v[6:7], v[22:23], v[50:51], v[6:7] op_sel_hi:[0,1,1]
	v_mov_b32_e32 v62, v67
	v_pk_fma_f32 v[6:7], v[54:55], v[62:63], v[6:7] op_sel_hi:[0,1,1]
	v_pk_add_f32 v[6:7], v[52:53], v[6:7]
	ds_read_b128 v[50:53], v58 offset:31744
	ds_read_b128 v[60:63], v58 offset:32768
	s_waitcnt lgkmcnt(1)
	v_mov_b32_e32 v65, v50
	s_waitcnt lgkmcnt(0)
	v_mov_b32_e32 v50, v61
	v_mov_b32_e32 v64, v60
	v_pk_mul_f32 v[50:51], v[12:13], v[50:51] op_sel_hi:[0,1]
	v_pk_fma_f32 v[20:21], v[20:21], v[64:65], v[50:51] op_sel_hi:[0,1,1]
	v_mov_b32_e32 v50, v62
	v_mov_b32_e32 v51, v52
	v_pk_fma_f32 v[20:21], v[22:23], v[50:51], v[20:21] op_sel_hi:[0,1,1]
	v_mov_b32_e32 v52, v63
	v_pk_fma_f32 v[20:21], v[54:55], v[52:53], v[20:21] op_sel_hi:[0,1,1]
	v_pk_add_f32 v[18:19], v[18:19], v[20:21]
	s_waitcnt vmcnt(0)
	v_mov_b32_e32 v22, v240
	v_mov_b32_e32 v23, v241
	v_pk_mul_f32 v[2:3], v[22:23], v[2:3]
	v_mov_b32_e32 v20, v242
	v_mov_b32_e32 v21, v243
	v_add_f32_e32 v2, v2, v3
	v_mov_b32_e32 v54, v23
	v_cmp_ge_i32_e32 vcc, v57, v56
	v_lshl_add_u64 v[16:17], v[16:17], 0, s[22:23]
	s_or_b64 s[6:7], vcc, s[6:7]
	v_pk_mul_f32 v[4:5], v[20:21], v[4:5]
	s_nop 0
	v_add_f32_e32 v2, v2, v4
	v_add_f32_e32 v2, v2, v5
	v_add_f32_e32 v59, v59, v2
	ds_read_b128 v[2:5], v58 offset:1040
	ds_read_b128 v[50:53], v58 offset:2064
	v_mov_b32_e32 v12, v21
	s_waitcnt lgkmcnt(1)
	v_mov_b32_e32 v61, v2
	s_waitcnt lgkmcnt(0)
	v_mov_b32_e32 v2, v51
	v_mov_b32_e32 v60, v50
	v_pk_mul_f32 v[2:3], v[54:55], v[2:3] op_sel_hi:[0,1]
	v_pk_fma_f32 v[2:3], v[22:23], v[60:61], v[2:3] op_sel_hi:[0,1,1]
	v_mov_b32_e32 v50, v52
	v_mov_b32_e32 v51, v4
	v_pk_fma_f32 v[2:3], v[20:21], v[50:51], v[2:3] op_sel_hi:[0,1,1]
	v_mov_b32_e32 v4, v53
	v_pk_fma_f32 v[2:3], v[12:13], v[4:5], v[2:3] op_sel_hi:[0,1,1]
	v_pk_add_f32 v[24:25], v[24:25], v[2:3]
	ds_read_b128 v[2:5], v58 offset:3088
	ds_read_b128 v[50:53], v58 offset:4112
	s_waitcnt lgkmcnt(1)
	v_mov_b32_e32 v61, v2
	s_waitcnt lgkmcnt(0)
; __device__ __forceinline__ void mod_item(const Params& p, int item, char* lds) {
;     ...
; #pragma unroll
;     for (int b = 0; b < 33; ++b) {
;       const float4 sv = *(const float4*)(s + b * 256 + k);
;       acc[b] += sv.x * w0 + sv.y * w1 + sv.z * w2 + sv.w * w3;
;     }
	v_mov_b32_e32 v2, v51
	v_mov_b32_e32 v60, v50
	v_pk_mul_f32 v[2:3], v[54:55], v[2:3] op_sel_hi:[0,1]
	v_pk_fma_f32 v[2:3], v[22:23], v[60:61], v[2:3] op_sel_hi:[0,1,1]
	v_mov_b32_e32 v50, v52
	v_mov_b32_e32 v51, v4
	v_pk_fma_f32 v[2:3], v[20:21], v[50:51], v[2:3] op_sel_hi:[0,1,1]
	v_mov_b32_e32 v4, v53
	v_pk_fma_f32 v[2:3], v[12:13], v[4:5], v[2:3] op_sel_hi:[0,1,1]
	v_pk_add_f32 v[26:27], v[26:27], v[2:3]
	ds_read_b128 v[2:5], v58 offset:5136
	ds_read_b128 v[50:53], v58 offset:6160
	s_waitcnt lgkmcnt(1)
	v_mov_b32_e32 v61, v2
	s_waitcnt lgkmcnt(0)
	v_mov_b32_e32 v2, v51
	v_mov_b32_e32 v60, v50
	v_pk_mul_f32 v[2:3], v[54:55], v[2:3] op_sel_hi:[0,1]
	v_pk_fma_f32 v[2:3], v[22:23], v[60:61], v[2:3] op_sel_hi:[0,1,1]
	v_mov_b32_e32 v50, v52
	v_mov_b32_e32 v51, v4
	v_pk_fma_f32 v[2:3], v[20:21], v[50:51], v[2:3] op_sel_hi:[0,1,1]
	v_mov_b32_e32 v4, v53
	v_pk_fma_f32 v[2:3], v[12:13], v[4:5], v[2:3] op_sel_hi:[0,1,1]
	v_pk_add_f32 v[28:29], v[28:29], v[2:3]
	ds_read_b128 v[2:5], v58 offset:7184
	ds_read_b128 v[50:53], v58 offset:8208
	s_waitcnt lgkmcnt(1)
	v_mov_b32_e32 v61, v2
	s_waitcnt lgkmcnt(0)
	v_mov_b32_e32 v2, v51
	v_mov_b32_e32 v60, v50
	v_pk_mul_f32 v[2:3], v[54:55], v[2:3] op_sel_hi:[0,1]
	v_pk_fma_f32 v[2:3], v[22:23], v[60:61], v[2:3] op_sel_hi:[0,1,1]
	v_mov_b32_e32 v50, v52
	v_mov_b32_e32 v51, v4
	v_pk_fma_f32 v[2:3], v[20:21], v[50:51], v[2:3] op_sel_hi:[0,1,1]
	v_mov_b32_e32 v4, v53
	v_pk_fma_f32 v[2:3], v[12:13], v[4:5], v[2:3] op_sel_hi:[0,1,1]
	v_pk_add_f32 v[30:31], v[30:31], v[2:3]
	ds_read_b128 v[2:5], v58 offset:9232
	ds_read_b128 v[50:53], v58 offset:10256
	s_waitcnt lgkmcnt(1)
	v_mov_b32_e32 v61, v2
	s_waitcnt lgkmcnt(0)
	v_mov_b32_e32 v2, v51
	v_mov_b32_e32 v60, v50
	v_pk_mul_f32 v[2:3], v[54:55], v[2:3] op_sel_hi:[0,1]
	v_pk_fma_f32 v[2:3], v[22:23], v[60:61], v[2:3] op_sel_hi:[0,1,1]
	v_mov_b32_e32 v50, v52
	v_mov_b32_e32 v51, v4
	v_pk_fma_f32 v[2:3], v[20:21], v[50:51], v[2:3] op_sel_hi:[0,1,1]
	v_mov_b32_e32 v4, v53
	v_pk_fma_f32 v[2:3], v[12:13], v[4:5], v[2:3] op_sel_hi:[0,1,1]
	v_pk_add_f32 v[32:33], v[32:33], v[2:3]
	ds_read_b128 v[2:5], v58 offset:11280
	ds_read_b128 v[50:53], v58 offset:12304
	s_waitcnt lgkmcnt(1)
	v_mov_b32_e32 v61, v2
	s_waitcnt lgkmcnt(0)
	v_mov_b32_e32 v2, v51
	v_mov_b32_e32 v60, v50
	v_pk_mul_f32 v[2:3], v[54:55], v[2:3] op_sel_hi:[0,1]
	v_pk_fma_f32 v[2:3], v[22:23], v[60:61], v[2:3] op_sel_hi:[0,1,1]
	v_mov_b32_e32 v50, v52
	v_mov_b32_e32 v51, v4
	v_pk_fma_f32 v[2:3], v[20:21], v[50:51], v[2:3] op_sel_hi:[0,1,1]
	v_mov_b32_e32 v4, v53
	v_pk_fma_f32 v[2:3], v[12:13], v[4:5], v[2:3] op_sel_hi:[0,1,1]
	v_pk_add_f32 v[34:35], v[34:35], v[2:3]
	ds_read_b128 v[2:5], v58 offset:13328
	ds_read_b128 v[50:53], v58 offset:14352
	s_waitcnt lgkmcnt(1)
	v_mov_b32_e32 v61, v2
	s_waitcnt lgkmcnt(0)
	v_mov_b32_e32 v2, v51
	v_mov_b32_e32 v60, v50
	v_pk_mul_f32 v[2:3], v[54:55], v[2:3] op_sel_hi:[0,1]
	v_pk_fma_f32 v[2:3], v[22:23], v[60:61], v[2:3] op_sel_hi:[0,1,1]
	v_mov_b32_e32 v50, v52
	v_mov_b32_e32 v51, v4
	v_pk_fma_f32 v[2:3], v[20:21], v[50:51], v[2:3] op_sel_hi:[0,1,1]
	v_mov_b32_e32 v4, v53
	v_pk_fma_f32 v[2:3], v[12:13], v[4:5], v[2:3] op_sel_hi:[0,1,1]
	v_pk_add_f32 v[36:37], v[36:37], v[2:3]
	ds_read_b128 v[2:5], v58 offset:15376
	ds_read_b128 v[50:53], v58 offset:16400
	s_waitcnt lgkmcnt(1)
	v_mov_b32_e32 v61, v2
	s_waitcnt lgkmcnt(0)
	v_mov_b32_e32 v2, v51
	v_mov_b32_e32 v60, v50
	v_pk_mul_f32 v[2:3], v[54:55], v[2:3] op_sel_hi:[0,1]
	v_pk_fma_f32 v[2:3], v[22:23], v[60:61], v[2:3] op_sel_hi:[0,1,1]
	v_mov_b32_e32 v50, v52
	v_mov_b32_e32 v51, v4
	v_pk_fma_f32 v[2:3], v[20:21], v[50:51], v[2:3] op_sel_hi:[0,1,1]
	v_mov_b32_e32 v4, v53
	v_pk_fma_f32 v[2:3], v[12:13], v[4:5], v[2:3] op_sel_hi:[0,1,1]
	v_pk_add_f32 v[40:41], v[40:41], v[2:3]
	ds_read_b128 v[2:5], v58 offset:17424
	ds_read_b128 v[50:53], v58 offset:18448
	s_waitcnt lgkmcnt(1)
	v_mov_b32_e32 v61, v2
	s_waitcnt lgkmcnt(0)
	v_mov_b32_e32 v2, v51
	v_mov_b32_e32 v60, v50
	v_pk_mul_f32 v[2:3], v[54:55], v[2:3] op_sel_hi:[0,1]
	v_pk_fma_f32 v[2:3], v[22:23], v[60:61], v[2:3] op_sel_hi:[0,1,1]
	v_mov_b32_e32 v50, v52
	v_mov_b32_e32 v51, v4
	v_pk_fma_f32 v[2:3], v[20:21], v[50:51], v[2:3] op_sel_hi:[0,1,1]
	v_mov_b32_e32 v4, v53
	v_pk_fma_f32 v[2:3], v[12:13], v[4:5], v[2:3] op_sel_hi:[0,1,1]
	v_pk_add_f32 v[42:43], v[42:43], v[2:3]
	ds_read_b128 v[2:5], v58 offset:19472
	ds_read_b128 v[50:53], v58 offset:20496
	s_waitcnt lgkmcnt(1)
; __device__ __forceinline__ void mod_item(const Params& p, int item, char* lds) {
;     ...
; #pragma unroll 2
;   for (int k = k0; k < k0 + 32; k += 4) {
;     const size_t kg = (size_t)(kq * 256 + k);
;     const float w0 = wmod[kg * 6144 + col], w1 = wmod[(kg + 1) * 6144 + col];
;     const float w2 = wmod[(kg + 2) * 6144 + col], w3 = wmod[(kg + 3) * 6144 + col];
; #pragma unroll
;     for (int b = 0; b < 33; ++b) {
;       const float4 sv = *(const float4*)(s + b * 256 + k);
;       acc[b] += sv.x * w0 + sv.y * w1 + sv.z * w2 + sv.w * w3;
;     }
;   }
;   const float bias = (wave == 0 && kq == 0) ? bmod[col] : 0.f;
	v_mov_b32_e32 v61, v2
	s_waitcnt lgkmcnt(0)
	v_mov_b32_e32 v2, v51
	v_mov_b32_e32 v60, v50
	v_pk_mul_f32 v[2:3], v[54:55], v[2:3] op_sel_hi:[0,1]
	v_pk_fma_f32 v[2:3], v[22:23], v[60:61], v[2:3] op_sel_hi:[0,1,1]
	v_mov_b32_e32 v50, v52
	v_mov_b32_e32 v51, v4
	v_pk_fma_f32 v[2:3], v[20:21], v[50:51], v[2:3] op_sel_hi:[0,1,1]
	v_mov_b32_e32 v4, v53
	v_pk_fma_f32 v[2:3], v[12:13], v[4:5], v[2:3] op_sel_hi:[0,1,1]
	v_pk_add_f32 v[48:49], v[48:49], v[2:3]
	ds_read_b128 v[2:5], v58 offset:21520
	ds_read_b128 v[50:53], v58 offset:22544
	s_waitcnt lgkmcnt(1)
	v_mov_b32_e32 v61, v2
	s_waitcnt lgkmcnt(0)
	v_mov_b32_e32 v2, v51
	v_mov_b32_e32 v60, v50
	v_pk_mul_f32 v[2:3], v[54:55], v[2:3] op_sel_hi:[0,1]
	v_pk_fma_f32 v[2:3], v[22:23], v[60:61], v[2:3] op_sel_hi:[0,1,1]
	v_mov_b32_e32 v50, v52
	v_mov_b32_e32 v51, v4
	v_pk_fma_f32 v[2:3], v[20:21], v[50:51], v[2:3] op_sel_hi:[0,1,1]
	v_mov_b32_e32 v4, v53
	v_pk_fma_f32 v[2:3], v[12:13], v[4:5], v[2:3] op_sel_hi:[0,1,1]
	v_pk_add_f32 v[46:47], v[46:47], v[2:3]
	ds_read_b128 v[2:5], v58 offset:23568
	ds_read_b128 v[50:53], v58 offset:24592
	s_waitcnt lgkmcnt(1)
	v_mov_b32_e32 v61, v2
	s_waitcnt lgkmcnt(0)
	v_mov_b32_e32 v2, v51
	v_mov_b32_e32 v60, v50
	v_pk_mul_f32 v[2:3], v[54:55], v[2:3] op_sel_hi:[0,1]
	v_pk_fma_f32 v[2:3], v[22:23], v[60:61], v[2:3] op_sel_hi:[0,1,1]
	v_mov_b32_e32 v50, v52
	v_mov_b32_e32 v51, v4
	v_pk_fma_f32 v[2:3], v[20:21], v[50:51], v[2:3] op_sel_hi:[0,1,1]
	v_mov_b32_e32 v4, v53
	v_pk_fma_f32 v[2:3], v[12:13], v[4:5], v[2:3] op_sel_hi:[0,1,1]
	v_pk_add_f32 v[44:45], v[44:45], v[2:3]
	ds_read_b128 v[2:5], v58 offset:25616
	ds_read_b128 v[50:53], v58 offset:26640
	s_waitcnt lgkmcnt(1)
	v_mov_b32_e32 v61, v2
	s_waitcnt lgkmcnt(0)
	v_mov_b32_e32 v2, v51
	v_mov_b32_e32 v60, v50
	v_pk_mul_f32 v[2:3], v[54:55], v[2:3] op_sel_hi:[0,1]
	v_pk_fma_f32 v[2:3], v[22:23], v[60:61], v[2:3] op_sel_hi:[0,1,1]
	v_mov_b32_e32 v50, v52
	v_mov_b32_e32 v51, v4
	v_pk_fma_f32 v[2:3], v[20:21], v[50:51], v[2:3] op_sel_hi:[0,1,1]
	v_mov_b32_e32 v4, v53
	v_pk_fma_f32 v[2:3], v[12:13], v[4:5], v[2:3] op_sel_hi:[0,1,1]
	v_pk_add_f32 v[38:39], v[38:39], v[2:3]
	ds_read_b128 v[2:5], v58 offset:27664
	ds_read_b128 v[50:53], v58 offset:28688
	s_waitcnt lgkmcnt(1)
	v_mov_b32_e32 v61, v2
	s_waitcnt lgkmcnt(0)
	v_mov_b32_e32 v2, v51
	v_mov_b32_e32 v60, v50
	v_pk_mul_f32 v[2:3], v[54:55], v[2:3] op_sel_hi:[0,1]
	v_pk_fma_f32 v[2:3], v[22:23], v[60:61], v[2:3] op_sel_hi:[0,1,1]
	v_mov_b32_e32 v50, v52
	v_mov_b32_e32 v51, v4
	v_pk_fma_f32 v[2:3], v[20:21], v[50:51], v[2:3] op_sel_hi:[0,1,1]
	v_mov_b32_e32 v4, v53
	v_pk_fma_f32 v[2:3], v[12:13], v[4:5], v[2:3] op_sel_hi:[0,1,1]
	v_pk_add_f32 v[50:51], v[8:9], v[2:3]
	ds_read_b128 v[2:5], v58 offset:29712
	ds_read_b128 v[60:63], v58 offset:30736
	s_waitcnt lgkmcnt(1)
	v_mov_b32_e32 v9, v2
	s_waitcnt lgkmcnt(0)
	v_mov_b32_e32 v2, v61
	v_mov_b32_e32 v8, v60
	v_pk_mul_f32 v[2:3], v[54:55], v[2:3] op_sel_hi:[0,1]
	v_pk_fma_f32 v[2:3], v[22:23], v[8:9], v[2:3] op_sel_hi:[0,1,1]
	v_mov_b32_e32 v8, v62
	v_mov_b32_e32 v9, v4
	v_pk_fma_f32 v[2:3], v[20:21], v[8:9], v[2:3] op_sel_hi:[0,1,1]
	v_mov_b32_e32 v4, v63
	v_pk_fma_f32 v[2:3], v[12:13], v[4:5], v[2:3] op_sel_hi:[0,1,1]
	v_pk_add_f32 v[52:53], v[6:7], v[2:3]
	ds_read_b128 v[2:5], v58 offset:31760
	ds_read_b128 v[6:9], v58 offset:32784
	v_add_u32_e32 v58, 32, v58
	s_waitcnt lgkmcnt(1)
	v_mov_b32_e32 v61, v2
	s_waitcnt lgkmcnt(0)
	v_mov_b32_e32 v2, v7
	v_mov_b32_e32 v60, v6
	v_pk_mul_f32 v[2:3], v[54:55], v[2:3] op_sel_hi:[0,1]
	v_pk_fma_f32 v[2:3], v[22:23], v[60:61], v[2:3] op_sel_hi:[0,1,1]
	v_mov_b32_e32 v6, v8
	v_mov_b32_e32 v7, v4
	v_pk_fma_f32 v[2:3], v[20:21], v[6:7], v[2:3] op_sel_hi:[0,1,1]
	v_mov_b32_e32 v4, v9
	v_pk_fma_f32 v[2:3], v[12:13], v[4:5], v[2:3] op_sel_hi:[0,1,1]
	v_pk_add_f32 v[18:19], v[18:19], v[2:3]
	s_andn2_b64 exec, exec, s[6:7]
	s_cbranch_execnz .LBB0_22
	s_or_b64 exec, exec, s[6:7]
	s_lshl_b32 s6, s52, 4
	s_andn2_b32 s6, s6, 63
	s_cmp_eq_u32 s53, 0
	v_or_b32_e32 v2, s6, v15
	v_cmp_gt_u32_e32 vcc, 64, v14
	s_cselect_b64 s[6:7], -1, 0
	v_ashrrev_i32_e32 v3, 31, v2
	s_and_b64 s[8:9], s[6:7], vcc
	v_mov_b32_e32 v4, 0
	s_and_saveexec_b64 s[6:7], s[8:9]
	s_cbranch_execz .LBB0_8
	v_lshl_add_u64 v[4:5], v[2:3], 2, s[20:21]
	global_load_dword v4, v[4:5], off
	s_branch .LBB0_8
